# rescaled RWKV scan + helper: key L2-norm inverse by v_rsq_f32(max(ss,1e-24)) instead of the IEEE sqrt+div sequence (f32, ~35 fewer helper instructions per half-chunk)
# speedup vs baseline: 1.0024x; 1.0024x over previous
; __device__ __forceinline__ float sigm(float x) { return __builtin_amdgcn_rcpf(1.f + __expf(-x)); }
; template <int CTRL> __device__ __forceinline__ float dppf(float x) { return __builtin_bit_cast(float, __builtin_amdgcn_update_dpp(0, __builtin_bit_cast(int, x), CTRL, 0xF, 0xF, false)); }
; #define LDS_BAR() asm volatile("s_waitcnt lgkmcnt(0)\n\ts_barrier" ::: "memory")
; __device__ __forceinline__ void phase_rwkv_scan(const Fr& F, int jr) {
;     ...
;                     Wv[pp * 64 + hk] = __expf(-0.60653066f * sigm(w0v[hh] + cw[reg]));
;                     Av[pp * 64 + hk] = sigm(a0v[hh] + ca[reg]); }
;             }
;             LDS_BAR();
;             {
;                 const float kr[8] = {lo_bf(kw.x), hi_bf(kw.x), lo_bf(kw.y), hi_bf(kw.y), lo_bf(kw.z), hi_bf(kw.z), lo_bf(kw.w), hi_bf(kw.w)};
;                 const float rr[8] = {lo_bf(rw.x), hi_bf(rw.x), lo_bf(rw.y), hi_bf(rw.y), lo_bf(rw.z), hi_bf(rw.z), lo_bf(rw.w), hi_bf(rw.w)};
;                 float kq[8]; float ss = 0.f, bon = 0.f;
; #pragma unroll
;                 for (int i = 0; i < 8; ++i) { kq[i] = kr[i] * kkc[i]; ss += kq[i] * kq[i]; bon += rr[i] * kr[i] * rkc[i]; }
;                 ss += dppf<0xB1>(ss); ss += dppf<0x4E>(ss); ss += dppf<0x141>(ss); bon += dppf<0xB1>(bon); bon += dppf<0x4E>(bon); bon += dppf<0x141>(bon);
;                 if (s == 0 && half == 0 && j8 == 0) Bon[((size_t)b * TB + tokof(s, chunk * 64 + p2)) * 16 + h] = bon;
;                 const float inv = 1.f / fmaxf(sqrtf(ss), 1e-12f);
.Lrw0_hnl0:
	v_mov_b32_e32 v196, v232
	s_nop 1
	v_permlane16_swap_b32_e32 v232, v196
	s_nop 1
	v_add_f32_e32 v232, v232, v196
	v_mov_b32_e32 v196, v232
	s_nop 1
	v_permlane32_swap_b32_e32 v232, v196
	s_nop 1
	v_add_f32_e32 v232, v232, v196
	v_max_f32_e32 v196, 0x179abe15, v232
	v_rsq_f32_e32 v232, v196
	v_pk_add_f32 v[136:137], v[32:33], v[136:137]
	v_pk_add_f32 v[138:139], v[34:35], v[138:139]
	v_pk_add_f32 v[144:145], v[40:41], v[144:145]
	v_pk_add_f32 v[146:147], v[42:43], v[146:147]
	v_pk_add_f32 v[140:141], v[36:37], v[140:141]
	v_pk_add_f32 v[142:143], v[38:39], v[142:143]
	v_pk_add_f32 v[148:149], v[44:45], v[148:149]
	v_pk_add_f32 v[150:151], v[46:47], v[150:151]
	v_pk_mul_f32 v[136:137], v[136:137], v[122:123]
	v_pk_mul_f32 v[138:139], v[138:139], v[122:123]
	v_pk_mul_f32 v[144:145], v[144:145], v[122:123]
	v_pk_mul_f32 v[146:147], v[146:147], v[122:123]
	v_pk_mul_f32 v[140:141], v[140:141], v[122:123]
	v_pk_mul_f32 v[142:143], v[142:143], v[122:123]
	v_pk_mul_f32 v[148:149], v[148:149], v[122:123]
	v_pk_mul_f32 v[150:151], v[150:151], v[122:123]
	v_exp_f32_e32 v136, v136
	v_exp_f32_e32 v137, v137
	v_exp_f32_e32 v138, v138
	v_exp_f32_e32 v139, v139
	v_exp_f32_e32 v144, v144
	v_exp_f32_e32 v145, v145
	v_exp_f32_e32 v146, v146
	v_exp_f32_e32 v147, v147
	v_exp_f32_e32 v140, v140
	v_exp_f32_e32 v141, v141
	v_exp_f32_e32 v142, v142
	v_exp_f32_e32 v143, v143
	v_exp_f32_e32 v148, v148
	v_exp_f32_e32 v149, v149
	v_exp_f32_e32 v150, v150
	v_exp_f32_e32 v151, v151
	v_pk_add_f32 v[136:137], v[136:137], 1.0 op_sel_hi:[1,0]
	v_pk_add_f32 v[138:139], v[138:139], 1.0 op_sel_hi:[1,0]
	v_pk_add_f32 v[144:145], v[144:145], 1.0 op_sel_hi:[1,0]
	v_pk_add_f32 v[146:147], v[146:147], 1.0 op_sel_hi:[1,0]
	v_pk_add_f32 v[140:141], v[140:141], 1.0 op_sel_hi:[1,0]
	v_pk_add_f32 v[142:143], v[142:143], 1.0 op_sel_hi:[1,0]
	v_pk_add_f32 v[148:149], v[148:149], 1.0 op_sel_hi:[1,0]
	v_pk_add_f32 v[150:151], v[150:151], 1.0 op_sel_hi:[1,0]
	v_rcp_f32_e32 v136, v136
	v_rcp_f32_e32 v137, v137
	v_rcp_f32_e32 v138, v138
	v_rcp_f32_e32 v139, v139
	v_rcp_f32_e32 v144, v144
	v_rcp_f32_e32 v145, v145
	v_rcp_f32_e32 v146, v146
	v_rcp_f32_e32 v147, v147
	v_rcp_f32_e32 v140, v140
	v_rcp_f32_e32 v141, v141
	v_rcp_f32_e32 v142, v142
	v_rcp_f32_e32 v143, v143
	v_rcp_f32_e32 v148, v148
	v_rcp_f32_e32 v149, v149
	v_rcp_f32_e32 v150, v150
	v_rcp_f32_e32 v151, v151
	v_pk_mul_f32 v[136:137], v[136:137], v[124:125]
	v_pk_mul_f32 v[138:139], v[138:139], v[124:125]
	v_pk_mul_f32 v[140:141], v[140:141], v[124:125]
	v_pk_mul_f32 v[142:143], v[142:143], v[124:125]
	v_pk_mul_f32 v[236:237], v[136:137], v[126:127]
	v_pk_mul_f32 v[238:239], v[138:139], v[126:127]
	v_pk_mul_f32 v[240:241], v[140:141], v[126:127]
	v_pk_mul_f32 v[242:243], v[142:143], v[126:127]
	v_pk_mul_f32 v[136:137], v[136:137], v[126:127]
	v_pk_mul_f32 v[138:139], v[138:139], v[126:127]
	v_pk_mul_f32 v[140:141], v[140:141], v[126:127]
	v_pk_mul_f32 v[142:143], v[142:143], v[126:127]
	v_add_f32_dpp v136, v136, v136 row_shr:1 row_mask:0xf bank_mask:0xf
	v_add_f32_dpp v137, v137, v137 row_shr:1 row_mask:0xf bank_mask:0xf
	v_add_f32_dpp v138, v138, v138 row_shr:1 row_mask:0xf bank_mask:0xf
	v_add_f32_dpp v139, v139, v139 row_shr:1 row_mask:0xf bank_mask:0xf
	v_add_f32_dpp v140, v140, v140 row_shr:1 row_mask:0xf bank_mask:0xf
	v_add_f32_dpp v141, v141, v141 row_shr:1 row_mask:0xf bank_mask:0xf
	v_add_f32_dpp v142, v142, v142 row_shr:1 row_mask:0xf bank_mask:0xf
	v_add_f32_dpp v143, v143, v143 row_shr:1 row_mask:0xf bank_mask:0xf
	v_add_f32_dpp v136, v136, v136 row_shr:2 row_mask:0xf bank_mask:0xf
	v_add_f32_dpp v137, v137, v137 row_shr:2 row_mask:0xf bank_mask:0xf
	v_add_f32_dpp v138, v138, v138 row_shr:2 row_mask:0xf bank_mask:0xf
	v_add_f32_dpp v139, v139, v139 row_shr:2 row_mask:0xf bank_mask:0xf
	v_add_f32_dpp v140, v140, v140 row_shr:2 row_mask:0xf bank_mask:0xf
	v_add_f32_dpp v141, v141, v141 row_shr:2 row_mask:0xf bank_mask:0xf
	v_add_f32_dpp v142, v142, v142 row_shr:2 row_mask:0xf bank_mask:0xf
	v_add_f32_dpp v143, v143, v143 row_shr:2 row_mask:0xf bank_mask:0xf
	v_add_f32_dpp v136, v136, v136 row_shr:4 row_mask:0xf bank_mask:0xf
	v_add_f32_dpp v137, v137, v137 row_shr:4 row_mask:0xf bank_mask:0xf
	v_add_f32_dpp v138, v138, v138 row_shr:4 row_mask:0xf bank_mask:0xf
	v_add_f32_dpp v139, v139, v139 row_shr:4 row_mask:0xf bank_mask:0xf
	v_add_f32_dpp v140, v140, v140 row_shr:4 row_mask:0xf bank_mask:0xf
	v_add_f32_dpp v141, v141, v141 row_shr:4 row_mask:0xf bank_mask:0xf
	v_add_f32_dpp v142, v142, v142 row_shr:4 row_mask:0xf bank_mask:0xf
	v_add_f32_dpp v143, v143, v143 row_shr:4 row_mask:0xf bank_mask:0xf
; __device__ __forceinline__ void phase_rwkv_scan(const Fr& F, int jr) {
;     ...
;                 if (s == 0 && half == 0 && j8 == 0) Bon[((size_t)b * TB + tokof(s, chunk * 64 + p2)) * 16 + h] = bon;
;                 const float inv = 1.f / fmaxf(sqrtf(ss), 1e-12f);
;                 const f32x4 av0 = *(const f32x4*)(Av + p2 * 64 + hk0), av1 = *(const f32x4*)(Av + p2 * 64 + hk0 + 4);
;                 const float av[8] = {av0.x, av0.y, av0.z, av0.w, av1.x, av1.y, av1.z, av1.w};
;                 float o1[8], o2[8], o3[8];
; #pragma unroll
;                 for (int i = 0; i < 8; ++i) { const float kkv = kq[i] * inv; o1[i] = kkv; o2[i] = kkv * av[i]; o3[i] = kr[i] * (1.f + (av[i] - 1.f) * kac[i]); }
;                 const int o = p2 * 64 + hk0;
;                 *(f32x4*)(KK + o) = (f32x4){o1[0], o1[1], o1[2], o1[3]}; *(f32x4*)(KK + o + 4) = (f32x4){o1[4], o1[5], o1[6], o1[7]};
;                 *(f32x4*)(Bv + o) = (f32x4){o2[0], o2[1], o2[2], o2[3]}; *(f32x4*)(Bv + o + 4) = (f32x4){o2[4], o2[5], o2[6], o2[7]};
;                 *(f32x4*)(KD + o) = (f32x4){o3[0], o3[1], o3[2], o3[3]}; *(f32x4*)(KD + o + 4) = (f32x4){o3[4], o3[5], o3[6], o3[7]};
;                 *(f32x4*)(Rr + o) = (f32x4){rr[0], rr[1], rr[2], rr[3]}; *(f32x4*)(Rr + o + 4) = (f32x4){rr[4], rr[5], rr[6], rr[7]};
;                 *(f32x4*)(Vv + p2 * 32 + 4 * j8) = (f32x4){lo_bf(vw.x), hi_bf(vw.x), lo_bf(vw.y), hi_bf(vw.y)};
	v_add_f32_dpp v136, v136, v136 row_shr:8 row_mask:0xf bank_mask:0xf
	v_add_f32_dpp v137, v137, v137 row_shr:8 row_mask:0xf bank_mask:0xf
	v_add_f32_dpp v138, v138, v138 row_shr:8 row_mask:0xf bank_mask:0xf
	v_add_f32_dpp v139, v139, v139 row_shr:8 row_mask:0xf bank_mask:0xf
	v_add_f32_dpp v140, v140, v140 row_shr:8 row_mask:0xf bank_mask:0xf
	v_add_f32_dpp v141, v141, v141 row_shr:8 row_mask:0xf bank_mask:0xf
	v_add_f32_dpp v142, v142, v142 row_shr:8 row_mask:0xf bank_mask:0xf
	v_add_f32_dpp v143, v143, v143 row_shr:8 row_mask:0xf bank_mask:0xf
	v_pk_add_f32 v[236:237], v[136:137], v[236:237] neg_lo:[0,1] neg_hi:[0,1]
	v_pk_add_f32 v[238:239], v[138:139], v[238:239] neg_lo:[0,1] neg_hi:[0,1]
	v_pk_add_f32 v[240:241], v[140:141], v[240:241] neg_lo:[0,1] neg_hi:[0,1]
	v_pk_add_f32 v[242:243], v[142:143], v[242:243] neg_lo:[0,1] neg_hi:[0,1]
	v_exp_f32_e64 v244, -v136
	v_exp_f32_e64 v245, -v137
	v_exp_f32_e64 v246, -v138
	v_exp_f32_e64 v247, -v139
	v_exp_f32_e64 v248, -v140
	v_exp_f32_e64 v249, -v141
	v_exp_f32_e64 v250, -v142
	v_exp_f32_e64 v251, -v143
	v_exp_f32_e32 v236, v236
	v_exp_f32_e32 v237, v237
	v_exp_f32_e32 v238, v238
	v_exp_f32_e32 v239, v239
	v_exp_f32_e32 v240, v240
	v_exp_f32_e32 v241, v241
	v_exp_f32_e32 v242, v242
	v_exp_f32_e32 v243, v243
	v_exp_f32_e32 v136, v136
	v_exp_f32_e32 v137, v137
	v_exp_f32_e32 v138, v138
	v_exp_f32_e32 v139, v139
	v_exp_f32_e32 v140, v140
	v_exp_f32_e32 v141, v141
	v_exp_f32_e32 v142, v142
	v_exp_f32_e32 v143, v143
	v_pk_mul_f32 v[204:205], v[176:177], v[232:233] op_sel_hi:[1,0]
	v_pk_mul_f32 v[206:207], v[178:179], v[232:233] op_sel_hi:[1,0]
	v_pk_add_f32 v[212:213], v[144:145], -1.0 op_sel_hi:[1,0]
	v_pk_add_f32 v[214:215], v[146:147], -1.0 op_sel_hi:[1,0]
	v_pk_mul_f32 v[208:209], v[204:205], v[144:145]
	v_pk_mul_f32 v[210:211], v[206:207], v[146:147]
	v_pk_fma_f32 v[212:213], v[64:65], v[212:213], 1.0 op_sel_hi:[1,1,0]
	v_pk_fma_f32 v[214:215], v[66:67], v[214:215], 1.0 op_sel_hi:[1,1,0]
	ds_write_b128 v224, v[136:139] offset:0
	v_pk_mul_f32 v[204:205], v[204:205], v[236:237]
	v_pk_mul_f32 v[206:207], v[206:207], v[238:239]
	v_pk_mul_f32 v[212:213], v[212:213], v[152:153]
	v_pk_mul_f32 v[214:215], v[214:215], v[154:155]
	ds_write_b128 v224, v[204:207] offset:8704
	v_pk_mul_f32 v[208:209], v[208:209], v[244:245]
	v_pk_mul_f32 v[210:211], v[210:211], v[246:247]
	v_pk_mul_f32 v[196:197], v[168:169], v[136:137]
	v_pk_mul_f32 v[198:199], v[170:171], v[138:139]
	ds_write_b128 v224, v[208:211] offset:17408
	v_pk_mul_f32 v[212:213], v[212:213], v[244:245]
	v_pk_mul_f32 v[214:215], v[214:215], v[246:247]
	ds_write_b128 v224, v[196:199] offset:34816
	ds_write_b128 v224, v[212:215] offset:26112
	v_pk_mul_f32 v[204:205], v[180:181], v[232:233] op_sel_hi:[1,0]
	v_pk_mul_f32 v[206:207], v[182:183], v[232:233] op_sel_hi:[1,0]
	v_pk_add_f32 v[212:213], v[148:149], -1.0 op_sel_hi:[1,0]
	v_pk_add_f32 v[214:215], v[150:151], -1.0 op_sel_hi:[1,0]
	v_pk_mul_f32 v[208:209], v[204:205], v[148:149]
	v_pk_mul_f32 v[210:211], v[206:207], v[150:151]
	v_pk_fma_f32 v[212:213], v[68:69], v[212:213], 1.0 op_sel_hi:[1,1,0]
	v_pk_fma_f32 v[214:215], v[70:71], v[214:215], 1.0 op_sel_hi:[1,1,0]
	ds_write_b128 v224, v[140:143] offset:64
	v_pk_mul_f32 v[204:205], v[204:205], v[240:241]
	v_pk_mul_f32 v[206:207], v[206:207], v[242:243]
	v_pk_mul_f32 v[212:213], v[212:213], v[156:157]
	v_pk_mul_f32 v[214:215], v[214:215], v[158:159]
	ds_write_b128 v224, v[204:207] offset:8768
	v_pk_mul_f32 v[208:209], v[208:209], v[248:249]
	v_pk_mul_f32 v[210:211], v[210:211], v[250:251]
	v_pk_mul_f32 v[196:197], v[172:173], v[140:141]
	v_pk_mul_f32 v[198:199], v[174:175], v[142:143]
	ds_write_b128 v224, v[208:211] offset:17472
	v_pk_mul_f32 v[212:213], v[212:213], v[248:249]
	v_pk_mul_f32 v[214:215], v[214:215], v[250:251]
	ds_write_b128 v224, v[196:199] offset:34880
	ds_write_b128 v224, v[212:215] offset:26176
	v_mov_b32_e32 v204, v193
	v_mov_b32_e32 v205, v192
	v_mov_b32_e32 v206, v195
	v_mov_b32_e32 v207, v194
	ds_write_b64 v225, v[192:193] offset:43520
	ds_write_b64 v225, v[204:205] offset:43536
	ds_write_b64 v225, v[194:195] offset:43552
	ds_write_b64 v225, v[206:207] offset:43568
	s_cmp_eq_u32 s32, 0
	s_cbranch_scc1 .Lrw0_hnb0
	v_mov_b32_e32 v196, v234
	s_nop 1
	v_permlane16_swap_b32_e32 v234, v196
	s_nop 1
	v_add_f32_e32 v234, v234, v196
	v_mov_b32_e32 v196, v234
	s_nop 1
	v_permlane32_swap_b32_e32 v234, v196
	s_nop 1
	v_add_f32_e32 v234, v234, v196
	v_cmp_gt_u32_e32 vcc, 16, v130
	s_and_saveexec_b64 s[56:57], vcc
	global_store_dword v202, v234, s[44:45]
	s_mov_b64 exec, s[56:57]
